# v79 + grid-barrier wait loops poll back to back (no s_sleep between polls)
# speedup vs baseline: 1.0108x; 1.0108x over previous
.LBB0_11:
	s_nop 0
	global_load_dword v2, v0, s[8:9] offset:32 sc1
	s_waitcnt vmcnt(0)
	v_and_b32_e32 v2, 0xffff0000, v2
	v_cmp_ne_u32_e32 vcc, v2, v1
	s_or_b64 s[10:11], vcc, s[10:11]
	s_andn2_b64 exec, exec, s[10:11]
	s_cbranch_execnz .LBB0_11

.LBB0_68:
	global_load_dword v15, v16, s[10:11] sc1
	global_load_dword v0, v16, s[12:13] sc1
	global_load_dword v1, v16, s[14:15] sc1
	global_load_dword v2, v16, s[16:17] sc1
	global_load_dword v3, v16, s[18:19] sc1
	global_load_dword v4, v16, s[24:25] sc1
	global_load_dword v5, v16, s[26:27] sc1
	global_load_dword v6, v16, s[28:29] sc1
	global_load_dword v7, v16, s[30:31] sc1
	global_load_dword v8, v16, s[36:37] sc1
	global_load_dword v9, v16, s[38:39] sc1
	global_load_dword v10, v16, s[40:41] sc1
	global_load_dword v11, v16, s[42:43] sc1
	global_load_dword v12, v16, s[44:45] sc1
	global_load_dword v13, v16, s[48:49] sc1
	global_load_dword v14, v16, s[50:51] sc1
	s_mov_b64 s[52:53], -1
	s_mov_b64 s[54:55], -1
	s_waitcnt vmcnt(14)
	v_add_u32_e32 v17, v0, v15
	s_waitcnt vmcnt(13)
	v_add_u32_e32 v17, v17, v1
	s_waitcnt vmcnt(12)
	v_add_u32_e32 v17, v17, v2
	s_waitcnt vmcnt(11)
	v_add_u32_e32 v17, v17, v3
	s_waitcnt vmcnt(10)
	v_add_u32_e32 v17, v17, v4
	s_waitcnt vmcnt(9)
	v_add_u32_e32 v17, v17, v5
	s_waitcnt vmcnt(8)
	v_add_u32_e32 v17, v17, v6
	s_waitcnt vmcnt(7)
	v_add_u32_e32 v17, v17, v7
	s_waitcnt vmcnt(6)
	v_add_u32_e32 v17, v17, v8
	s_waitcnt vmcnt(5)
	v_add_u32_e32 v17, v17, v9
	s_waitcnt vmcnt(4)
	v_add_u32_e32 v17, v17, v10
	s_waitcnt vmcnt(3)
	v_add_u32_e32 v17, v17, v11
	s_waitcnt vmcnt(2)
	v_add_u32_e32 v17, v17, v12
	s_waitcnt vmcnt(1)
	v_add_u32_e32 v17, v17, v13
	s_waitcnt vmcnt(0)
	v_add_u32_e32 v17, v17, v14
	v_cmp_eq_u32_e32 vcc, s1, v17
	s_cbranch_vccnz .LBB0_67
	s_and_b32 s3, s2, 0xff
	s_cmp_eq_u32 s3, 0
	s_mov_b64 s[56:57], -1
	s_nop 0
	s_cbranch_scc0 .LBB0_72
	global_load_dword v17, v16, s[8:9] sc1
	s_waitcnt vmcnt(0)
	v_cmp_eq_u32_e32 vcc, 0, v17
	s_cbranch_vccnz .LBB0_74
	s_mov_b64 s[56:57], 0

.LBB0_86:
	s_and_b32 s1, s0, 0xff
	s_mov_b64 s[26:27], -1
	s_cmp_lg_u32 s1, 0
	s_mov_b64 s[30:31], -1
	s_nop 0
	s_cbranch_scc1 .LBB0_89
	global_load_dword v2, v0, s[14:15] sc1
	s_waitcnt vmcnt(0)
	v_cmp_eq_u32_e32 vcc, 0, v2
	s_cbranch_vccnz .LBB0_91
	s_mov_b64 s[30:31], 0
	s_mov_b64 s[28:29], -1

.LBB0_103:
	s_and_b32 s1, s0, 0xff
	s_cmp_lg_u32 s1, 0
	s_mov_b64 s[26:27], -1
	s_nop 0
	s_cbranch_scc1 .LBB0_106
	global_load_dword v1, v0, s[14:15] sc1
	s_waitcnt vmcnt(0)
	v_cmp_eq_u32_e32 vcc, 0, v1
	s_cbranch_vccnz .LBB0_108
	s_mov_b64 s[26:27], 0
	s_mov_b64 s[24:25], -1

.LBB0_204:
	global_load_dword v15, v16, s[8:9] sc1
	global_load_dword v0, v16, s[12:13] sc1
	global_load_dword v1, v16, s[14:15] sc1
	global_load_dword v2, v16, s[16:17] sc1
	global_load_dword v3, v16, s[18:19] sc1
	global_load_dword v4, v16, s[24:25] sc1
	global_load_dword v5, v16, s[26:27] sc1
	global_load_dword v6, v16, s[28:29] sc1
	global_load_dword v7, v16, s[30:31] sc1
	global_load_dword v8, v16, s[36:37] sc1
	global_load_dword v9, v16, s[38:39] sc1
	global_load_dword v10, v16, s[40:41] sc1
	global_load_dword v11, v16, s[42:43] sc1
	global_load_dword v12, v16, s[44:45] sc1
	global_load_dword v13, v16, s[48:49] sc1
	global_load_dword v14, v16, s[50:51] sc1
	s_mov_b64 s[52:53], -1
	s_mov_b64 s[54:55], -1
	s_waitcnt vmcnt(14)
	v_add_u32_e32 v17, v0, v15
	s_waitcnt vmcnt(13)
	v_add_u32_e32 v17, v17, v1
	s_waitcnt vmcnt(12)
	v_add_u32_e32 v17, v17, v2
	s_waitcnt vmcnt(11)
	v_add_u32_e32 v17, v17, v3
	s_waitcnt vmcnt(10)
	v_add_u32_e32 v17, v17, v4
	s_waitcnt vmcnt(9)
	v_add_u32_e32 v17, v17, v5
	s_waitcnt vmcnt(8)
	v_add_u32_e32 v17, v17, v6
	s_waitcnt vmcnt(7)
	v_add_u32_e32 v17, v17, v7
	s_waitcnt vmcnt(6)
	v_add_u32_e32 v17, v17, v8
	s_waitcnt vmcnt(5)
	v_add_u32_e32 v17, v17, v9
	s_waitcnt vmcnt(4)
	v_add_u32_e32 v17, v17, v10
	s_waitcnt vmcnt(3)
	v_add_u32_e32 v17, v17, v11
	s_waitcnt vmcnt(2)
	v_add_u32_e32 v17, v17, v12
	s_waitcnt vmcnt(1)
	v_add_u32_e32 v17, v17, v13
	s_waitcnt vmcnt(0)
	v_add_u32_e32 v17, v17, v14
	v_cmp_eq_u32_e32 vcc, s1, v17
	s_cbranch_vccnz .LBB0_203
	s_and_b32 s3, s2, 0xff
	s_cmp_eq_u32 s3, 0
	s_mov_b64 s[56:57], -1
	s_nop 0
	s_cbranch_scc0 .LBB0_208
	global_load_dword v17, v16, s[6:7] sc1
	s_waitcnt vmcnt(0)
	v_cmp_eq_u32_e32 vcc, 0, v17
	s_cbranch_vccnz .LBB0_210
	s_mov_b64 s[56:57], 0

.LBB0_487:
	global_load_dword v15, v16, s[10:11] sc1
	global_load_dword v0, v16, s[12:13] sc1
	global_load_dword v1, v16, s[14:15] sc1
	global_load_dword v2, v16, s[18:19] sc1
	global_load_dword v3, v16, s[24:25] sc1
	global_load_dword v4, v16, s[26:27] sc1
	global_load_dword v5, v16, s[36:37] sc1
	global_load_dword v6, v16, s[38:39] sc1
	global_load_dword v7, v16, s[48:49] sc1
	global_load_dword v8, v16, s[50:51] sc1
	global_load_dword v9, v16, s[52:53] sc1
	global_load_dword v10, v16, s[54:55] sc1
	global_load_dword v11, v16, s[56:57] sc1
	global_load_dword v12, v16, s[58:59] sc1
	global_load_dword v13, v16, s[60:61] sc1
	global_load_dword v14, v16, s[62:63] sc1
	s_mov_b64 s[64:65], -1
	s_mov_b64 s[66:67], -1
	s_waitcnt vmcnt(14)
	v_add_u32_e32 v17, v0, v15
	s_waitcnt vmcnt(13)
	v_add_u32_e32 v17, v17, v1
	s_waitcnt vmcnt(12)
	v_add_u32_e32 v17, v17, v2
	s_waitcnt vmcnt(11)
	v_add_u32_e32 v17, v17, v3
	s_waitcnt vmcnt(10)
	v_add_u32_e32 v17, v17, v4
	s_waitcnt vmcnt(9)
	v_add_u32_e32 v17, v17, v5
	s_waitcnt vmcnt(8)
	v_add_u32_e32 v17, v17, v6
	s_waitcnt vmcnt(7)
	v_add_u32_e32 v17, v17, v7
	s_waitcnt vmcnt(6)
	v_add_u32_e32 v17, v17, v8
	s_waitcnt vmcnt(5)
	v_add_u32_e32 v17, v17, v9
	s_waitcnt vmcnt(4)
	v_add_u32_e32 v17, v17, v10
	s_waitcnt vmcnt(3)
	v_add_u32_e32 v17, v17, v11
	s_waitcnt vmcnt(2)
	v_add_u32_e32 v17, v17, v12
	s_waitcnt vmcnt(1)
	v_add_u32_e32 v17, v17, v13
	s_waitcnt vmcnt(0)
	v_add_u32_e32 v17, v17, v14
	v_cmp_eq_u32_e32 vcc, s2, v17
	s_cbranch_vccnz .LBB0_486
	s_and_b32 s21, s20, 0xff
	s_cmp_eq_u32 s21, 0
	s_mov_b64 s[68:69], -1
	s_nop 0
	s_cbranch_scc0 .LBB0_491
	global_load_dword v17, v16, s[8:9] sc1
	s_waitcnt vmcnt(0)
	v_cmp_eq_u32_e32 vcc, 0, v17
	s_cbranch_vccnz .LBB0_493
	s_mov_b64 s[68:69], 0

.LBB0_505:
	s_and_b32 s2, s1, 0xff
	s_mov_b64 s[36:37], -1
	s_cmp_lg_u32 s2, 0
	s_mov_b64 s[48:49], -1
	s_nop 0
	s_cbranch_scc1 .LBB0_508
	global_load_dword v2, v0, s[14:15] sc1
	s_waitcnt vmcnt(0)
	v_cmp_eq_u32_e32 vcc, 0, v2
	s_cbranch_vccnz .LBB0_510
	s_mov_b64 s[48:49], 0
	s_mov_b64 s[38:39], -1

.LBB0_522:
	s_and_b32 s2, s1, 0xff
	s_cmp_lg_u32 s2, 0
	s_mov_b64 s[36:37], -1
	s_nop 0
	s_cbranch_scc1 .LBB0_525
	global_load_dword v1, v0, s[14:15] sc1
	s_waitcnt vmcnt(0)
	v_cmp_eq_u32_e32 vcc, 0, v1
	s_cbranch_vccnz .LBB0_527
	s_mov_b64 s[36:37], 0
	s_mov_b64 s[26:27], -1

.LBB0_547:
	global_load_dword v15, v16, s[12:13] sc1
	global_load_dword v0, v16, s[14:15] sc1
	global_load_dword v1, v16, s[16:17] sc1
	global_load_dword v2, v16, s[18:19] sc1
	global_load_dword v3, v16, s[24:25] sc1
	global_load_dword v4, v16, s[26:27] sc1
	global_load_dword v5, v16, s[36:37] sc1
	global_load_dword v6, v16, s[38:39] sc1
	global_load_dword v7, v16, s[50:51] sc1
	global_load_dword v8, v16, s[52:53] sc1
	global_load_dword v9, v16, s[54:55] sc1
	global_load_dword v10, v16, s[56:57] sc1
	global_load_dword v11, v16, s[58:59] sc1
	global_load_dword v12, v16, s[60:61] sc1
	global_load_dword v13, v16, s[62:63] sc1
	global_load_dword v14, v16, s[64:65] sc1
	s_mov_b64 s[66:67], -1
	s_mov_b64 s[68:69], -1
	s_waitcnt vmcnt(14)
	v_add_u32_e32 v17, v0, v15
	s_waitcnt vmcnt(13)
	v_add_u32_e32 v17, v17, v1
	s_waitcnt vmcnt(12)
	v_add_u32_e32 v17, v17, v2
	s_waitcnt vmcnt(11)
	v_add_u32_e32 v17, v17, v3
	s_waitcnt vmcnt(10)
	v_add_u32_e32 v17, v17, v4
	s_waitcnt vmcnt(9)
	v_add_u32_e32 v17, v17, v5
	s_waitcnt vmcnt(8)
	v_add_u32_e32 v17, v17, v6
	s_waitcnt vmcnt(7)
	v_add_u32_e32 v17, v17, v7
	s_waitcnt vmcnt(6)
	v_add_u32_e32 v17, v17, v8
	s_waitcnt vmcnt(5)
	v_add_u32_e32 v17, v17, v9
	s_waitcnt vmcnt(4)
	v_add_u32_e32 v17, v17, v10
	s_waitcnt vmcnt(3)
	v_add_u32_e32 v17, v17, v11
	s_waitcnt vmcnt(2)
	v_add_u32_e32 v17, v17, v12
	s_waitcnt vmcnt(1)
	v_add_u32_e32 v17, v17, v13
	s_waitcnt vmcnt(0)
	v_add_u32_e32 v17, v17, v14
	v_cmp_eq_u32_e32 vcc, s2, v17
	s_cbranch_vccnz .LBB0_546
	s_and_b32 s21, s20, 0xff
	s_cmp_eq_u32 s21, 0
	s_mov_b64 s[70:71], -1
	s_nop 0
	s_cbranch_scc0 .LBB0_551
	global_load_dword v17, v16, s[10:11] sc1
	s_waitcnt vmcnt(0)
	v_cmp_eq_u32_e32 vcc, 0, v17
	s_cbranch_vccnz .LBB0_553
	s_mov_b64 s[70:71], 0

.LBB0_565:
	s_and_b32 s2, s1, 0xff
	s_mov_b64 s[36:37], -1
	s_cmp_lg_u32 s2, 0
	s_mov_b64 s[50:51], -1
	s_nop 0
	s_cbranch_scc1 .LBB0_568
	global_load_dword v2, v0, s[16:17] sc1
	s_waitcnt vmcnt(0)
	v_cmp_eq_u32_e32 vcc, 0, v2
	s_cbranch_vccnz .LBB0_570
	s_mov_b64 s[50:51], 0
	s_mov_b64 s[38:39], -1

.LBB0_582:
	s_and_b32 s2, s1, 0xff
	s_cmp_lg_u32 s2, 0
	s_mov_b64 s[36:37], -1
	s_nop 0
	s_cbranch_scc1 .LBB0_585
	global_load_dword v1, v0, s[16:17] sc1
	s_waitcnt vmcnt(0)
	v_cmp_eq_u32_e32 vcc, 0, v1
	s_cbranch_vccnz .LBB0_587
	s_mov_b64 s[36:37], 0
	s_mov_b64 s[26:27], -1

.LBB0_834:
	global_load_dword v15, v16, s[8:9] sc1
	s_waitcnt lgkmcnt(0)
	global_load_dword v0, v16, s[10:11] sc1
	global_load_dword v1, v16, s[12:13] sc1
	global_load_dword v2, v16, s[14:15] sc1
	global_load_dword v3, v16, s[16:17] sc1
	global_load_dword v4, v16, s[24:25] sc1
	global_load_dword v5, v16, s[26:27] sc1
	global_load_dword v6, v16, s[30:31] sc1
	global_load_dword v7, v16, s[36:37] sc1
	global_load_dword v8, v16, s[38:39] sc1
	global_load_dword v9, v16, s[50:51] sc1
	global_load_dword v10, v16, s[52:53] sc1
	global_load_dword v11, v16, s[54:55] sc1
	global_load_dword v12, v16, s[56:57] sc1
	global_load_dword v13, v16, s[58:59] sc1
	global_load_dword v14, v16, s[60:61] sc1
	s_mov_b64 s[62:63], -1
	s_mov_b64 s[64:65], -1
	s_waitcnt vmcnt(14)
	v_add_u32_e32 v17, v0, v15
	s_waitcnt vmcnt(13)
	v_add_u32_e32 v17, v17, v1
	s_waitcnt vmcnt(12)
	v_add_u32_e32 v17, v17, v2
	s_waitcnt vmcnt(11)
	v_add_u32_e32 v17, v17, v3
	s_waitcnt vmcnt(10)
	v_add_u32_e32 v17, v17, v4
	s_waitcnt vmcnt(9)
	v_add_u32_e32 v17, v17, v5
	s_waitcnt vmcnt(8)
	v_add_u32_e32 v17, v17, v6
	s_waitcnt vmcnt(7)
	v_add_u32_e32 v17, v17, v7
	s_waitcnt vmcnt(6)
	v_add_u32_e32 v17, v17, v8
	s_waitcnt vmcnt(5)
	v_add_u32_e32 v17, v17, v9
	s_waitcnt vmcnt(4)
	v_add_u32_e32 v17, v17, v10
	s_waitcnt vmcnt(3)
	v_add_u32_e32 v17, v17, v11
	s_waitcnt vmcnt(2)
	v_add_u32_e32 v17, v17, v12
	s_waitcnt vmcnt(1)
	v_add_u32_e32 v17, v17, v13
	s_waitcnt vmcnt(0)
	v_add_u32_e32 v17, v17, v14
	v_cmp_eq_u32_e32 vcc, s1, v17
	s_cbranch_vccnz .LBB0_833
	s_and_b32 s20, s2, 0xff
	s_cmp_eq_u32 s20, 0
	s_mov_b64 s[66:67], -1
	s_nop 0
	s_cbranch_scc0 .LBB0_838
	global_load_dword v17, v16, s[6:7] sc1
	s_waitcnt vmcnt(0)
	v_cmp_eq_u32_e32 vcc, 0, v17
	s_cbranch_vccnz .LBB0_840
	s_mov_b64 s[66:67], 0

.LBB0_852:
	s_and_b32 s1, s0, 0xff
	s_mov_b64 s[26:27], -1
	s_cmp_lg_u32 s1, 0
	s_mov_b64 s[36:37], -1
	s_nop 0
	s_cbranch_scc1 .LBB0_855
	global_load_dword v2, v0, s[12:13] sc1
	s_waitcnt vmcnt(0)
	v_cmp_eq_u32_e32 vcc, 0, v2
	s_cbranch_vccnz .LBB0_857
	s_mov_b64 s[36:37], 0
	s_mov_b64 s[30:31], -1

.LBB0_869:
	s_and_b32 s1, s0, 0xff
	s_cmp_lg_u32 s1, 0
	s_mov_b64 s[26:27], -1
	s_nop 0
	s_cbranch_scc1 .LBB0_872
	global_load_dword v1, v0, s[12:13] sc1
	s_waitcnt vmcnt(0)
	v_cmp_eq_u32_e32 vcc, 0, v1
	s_cbranch_vccnz .LBB0_874
	s_mov_b64 s[26:27], 0
	s_mov_b64 s[24:25], -1

.LBB0_924:
	global_load_dword v15, v16, s[10:11] sc1
	s_waitcnt lgkmcnt(0)
	global_load_dword v0, v16, s[12:13] sc1
	global_load_dword v1, v16, s[16:17] sc1
	global_load_dword v2, v16, s[18:19] sc1
	global_load_dword v3, v16, s[24:25] sc1
	global_load_dword v4, v16, s[26:27] sc1
	global_load_dword v5, v16, s[30:31] sc1
	global_load_dword v6, v16, s[36:37] sc1
	global_load_dword v7, v16, s[38:39] sc1
	global_load_dword v8, v16, s[50:51] sc1
	global_load_dword v9, v16, s[52:53] sc1
	global_load_dword v10, v16, s[54:55] sc1
	global_load_dword v11, v16, s[56:57] sc1
	global_load_dword v12, v16, s[58:59] sc1
	global_load_dword v13, v16, s[60:61] sc1
	global_load_dword v14, v16, s[62:63] sc1
	s_mov_b64 s[64:65], -1
	s_mov_b64 s[66:67], -1
	s_waitcnt vmcnt(14)
	v_add_u32_e32 v17, v0, v15
	s_waitcnt vmcnt(13)
	v_add_u32_e32 v17, v17, v1
	s_waitcnt vmcnt(12)
	v_add_u32_e32 v17, v17, v2
	s_waitcnt vmcnt(11)
	v_add_u32_e32 v17, v17, v3
	s_waitcnt vmcnt(10)
	v_add_u32_e32 v17, v17, v4
	s_waitcnt vmcnt(9)
	v_add_u32_e32 v17, v17, v5
	s_waitcnt vmcnt(8)
	v_add_u32_e32 v17, v17, v6
	s_waitcnt vmcnt(7)
	v_add_u32_e32 v17, v17, v7
	s_waitcnt vmcnt(6)
	v_add_u32_e32 v17, v17, v8
	s_waitcnt vmcnt(5)
	v_add_u32_e32 v17, v17, v9
	s_waitcnt vmcnt(4)
	v_add_u32_e32 v17, v17, v10
	s_waitcnt vmcnt(3)
	v_add_u32_e32 v17, v17, v11
	s_waitcnt vmcnt(2)
	v_add_u32_e32 v17, v17, v12
	s_waitcnt vmcnt(1)
	v_add_u32_e32 v17, v17, v13
	s_waitcnt vmcnt(0)
	v_add_u32_e32 v17, v17, v14
	v_cmp_eq_u32_e32 vcc, s1, v17
	s_cbranch_vccnz .LBB0_923
	s_and_b32 s20, s2, 0xff
	s_cmp_eq_u32 s20, 0
	s_mov_b64 s[68:69], -1
	s_nop 0
	s_cbranch_scc0 .LBB0_928
	global_load_dword v17, v16, s[8:9] sc1
	s_waitcnt vmcnt(0)
	v_cmp_eq_u32_e32 vcc, 0, v17
	s_cbranch_vccnz .LBB0_930
	s_mov_b64 s[68:69], 0

.LBB0_942:
	s_and_b32 s1, s0, 0xff
	s_mov_b64 s[30:31], -1
	s_cmp_lg_u32 s1, 0
	s_mov_b64 s[38:39], -1
	s_nop 0
	s_cbranch_scc1 .LBB0_945
	global_load_dword v2, v0, s[16:17] sc1
	s_waitcnt vmcnt(0)
	v_cmp_eq_u32_e32 vcc, 0, v2
	s_cbranch_vccnz .LBB0_947
	s_mov_b64 s[38:39], 0
	s_mov_b64 s[36:37], -1

.LBB0_959:
	s_and_b32 s1, s0, 0xff
	s_cmp_lg_u32 s1, 0
	s_mov_b64 s[30:31], -1
	s_nop 0
	s_cbranch_scc1 .LBB0_962
	global_load_dword v1, v0, s[16:17] sc1
	s_waitcnt vmcnt(0)
	v_cmp_eq_u32_e32 vcc, 0, v1
	s_cbranch_vccnz .LBB0_964
	s_mov_b64 s[30:31], 0
	s_mov_b64 s[26:27], -1

.LBB0_996:
	global_load_dword v15, v16, s[12:13] sc1
	s_waitcnt lgkmcnt(0)
	global_load_dword v0, v16, s[16:17] sc1
	global_load_dword v1, v16, s[18:19] sc1
	global_load_dword v2, v16, s[24:25] sc1
	global_load_dword v3, v16, s[26:27] sc1
	global_load_dword v4, v16, s[28:29] sc1
	global_load_dword v5, v16, s[30:31] sc1
	global_load_dword v6, v16, s[36:37] sc1
	global_load_dword v7, v16, s[38:39] sc1
	global_load_dword v8, v16, s[50:51] sc1
	global_load_dword v9, v16, s[52:53] sc1
	global_load_dword v10, v16, s[54:55] sc1
	global_load_dword v11, v16, s[56:57] sc1
	global_load_dword v12, v16, s[58:59] sc1
	global_load_dword v13, v16, s[60:61] sc1
	global_load_dword v14, v16, s[62:63] sc1
	s_mov_b64 s[64:65], -1
	s_mov_b64 s[66:67], -1
	s_waitcnt vmcnt(14)
	v_add_u32_e32 v17, v0, v15
	s_waitcnt vmcnt(13)
	v_add_u32_e32 v17, v17, v1
	s_waitcnt vmcnt(12)
	v_add_u32_e32 v17, v17, v2
	s_waitcnt vmcnt(11)
	v_add_u32_e32 v17, v17, v3
	s_waitcnt vmcnt(10)
	v_add_u32_e32 v17, v17, v4
	s_waitcnt vmcnt(9)
	v_add_u32_e32 v17, v17, v5
	s_waitcnt vmcnt(8)
	v_add_u32_e32 v17, v17, v6
	s_waitcnt vmcnt(7)
	v_add_u32_e32 v17, v17, v7
	s_waitcnt vmcnt(6)
	v_add_u32_e32 v17, v17, v8
	s_waitcnt vmcnt(5)
	v_add_u32_e32 v17, v17, v9
	s_waitcnt vmcnt(4)
	v_add_u32_e32 v17, v17, v10
	s_waitcnt vmcnt(3)
	v_add_u32_e32 v17, v17, v11
	s_waitcnt vmcnt(2)
	v_add_u32_e32 v17, v17, v12
	s_waitcnt vmcnt(1)
	v_add_u32_e32 v17, v17, v13
	s_waitcnt vmcnt(0)
	v_add_u32_e32 v17, v17, v14
	v_cmp_eq_u32_e32 vcc, s1, v17
	s_cbranch_vccnz .LBB0_995
	s_and_b32 s20, s2, 0xff
	s_cmp_eq_u32 s20, 0
	s_mov_b64 s[68:69], -1
	s_nop 0
	s_cbranch_scc0 .LBB0_1000
	global_load_dword v17, v16, s[10:11] sc1
	s_waitcnt vmcnt(0)
	v_cmp_eq_u32_e32 vcc, 0, v17
	s_cbranch_vccnz .LBB0_1002
	s_mov_b64 s[68:69], 0

.LBB0_1014:
	s_and_b32 s1, s0, 0xff
	s_mov_b64 s[30:31], -1
	s_cmp_lg_u32 s1, 0
	s_mov_b64 s[38:39], -1
	s_nop 0
	s_cbranch_scc1 .LBB0_1017
	global_load_dword v2, v0, s[18:19] sc1
	s_waitcnt vmcnt(0)
	v_cmp_eq_u32_e32 vcc, 0, v2
	s_cbranch_vccnz .LBB0_1019
	s_mov_b64 s[38:39], 0
	s_mov_b64 s[36:37], -1

.LBB0_1031:
	s_and_b32 s1, s0, 0xff
	s_cmp_lg_u32 s1, 0
	s_mov_b64 s[30:31], -1
	s_nop 0
	s_cbranch_scc1 .LBB0_1034
	global_load_dword v1, v0, s[18:19] sc1
	s_waitcnt vmcnt(0)
	v_cmp_eq_u32_e32 vcc, 0, v1
	s_cbranch_vccnz .LBB0_1036
	s_mov_b64 s[30:31], 0
	s_mov_b64 s[28:29], -1

.LBB0_1086:
	global_load_dword v15, v16, s[14:15] sc1
	s_waitcnt lgkmcnt(0)
	global_load_dword v0, v16, s[16:17] sc1
	global_load_dword v1, v16, s[18:19] sc1
	global_load_dword v2, v16, s[24:25] sc1
	global_load_dword v3, v16, s[26:27] sc1
	global_load_dword v4, v16, s[28:29] sc1
	global_load_dword v5, v16, s[30:31] sc1
	global_load_dword v6, v16, s[36:37] sc1
	global_load_dword v7, v16, s[38:39] sc1
	global_load_dword v8, v16, s[50:51] sc1
	global_load_dword v9, v16, s[52:53] sc1
	global_load_dword v10, v16, s[54:55] sc1
	global_load_dword v11, v16, s[56:57] sc1
	global_load_dword v12, v16, s[58:59] sc1
	global_load_dword v13, v16, s[60:61] sc1
	global_load_dword v14, v16, s[62:63] sc1
	s_mov_b64 s[64:65], -1
	s_mov_b64 s[66:67], -1
	s_waitcnt vmcnt(14)
	v_add_u32_e32 v17, v0, v15
	s_waitcnt vmcnt(13)
	v_add_u32_e32 v17, v17, v1
	s_waitcnt vmcnt(12)
	v_add_u32_e32 v17, v17, v2
	s_waitcnt vmcnt(11)
	v_add_u32_e32 v17, v17, v3
	s_waitcnt vmcnt(10)
	v_add_u32_e32 v17, v17, v4
	s_waitcnt vmcnt(9)
	v_add_u32_e32 v17, v17, v5
	s_waitcnt vmcnt(8)
	v_add_u32_e32 v17, v17, v6
	s_waitcnt vmcnt(7)
	v_add_u32_e32 v17, v17, v7
	s_waitcnt vmcnt(6)
	v_add_u32_e32 v17, v17, v8
	s_waitcnt vmcnt(5)
	v_add_u32_e32 v17, v17, v9
	s_waitcnt vmcnt(4)
	v_add_u32_e32 v17, v17, v10
	s_waitcnt vmcnt(3)
	v_add_u32_e32 v17, v17, v11
	s_waitcnt vmcnt(2)
	v_add_u32_e32 v17, v17, v12
	s_waitcnt vmcnt(1)
	v_add_u32_e32 v17, v17, v13
	s_waitcnt vmcnt(0)
	v_add_u32_e32 v17, v17, v14
	v_cmp_eq_u32_e32 vcc, s1, v17
	s_cbranch_vccnz .LBB0_1085
	s_and_b32 s20, s2, 0xff
	s_cmp_eq_u32 s20, 0
	s_mov_b64 s[68:69], -1
	s_nop 0
	s_cbranch_scc0 .LBB0_1090
	global_load_dword v17, v16, s[10:11] sc1
	s_waitcnt vmcnt(0)
	v_cmp_eq_u32_e32 vcc, 0, v17
	s_cbranch_vccnz .LBB0_1092
	s_mov_b64 s[68:69], 0

.LBB0_1243:
	global_load_dword v15, v16, s[12:13] sc1
	s_waitcnt lgkmcnt(0)
	global_load_dword v0, v16, s[16:17] sc1
	global_load_dword v1, v16, s[18:19] sc1
	global_load_dword v2, v16, s[24:25] sc1
	global_load_dword v3, v16, s[26:27] sc1
	global_load_dword v4, v16, s[28:29] sc1
	global_load_dword v5, v16, s[30:31] sc1
	global_load_dword v6, v16, s[36:37] sc1
	global_load_dword v7, v16, s[38:39] sc1
	global_load_dword v8, v16, s[46:47] sc1
	global_load_dword v9, v16, s[50:51] sc1
	global_load_dword v10, v16, s[52:53] sc1
	global_load_dword v11, v16, s[54:55] sc1
	global_load_dword v12, v16, s[56:57] sc1
	global_load_dword v13, v16, s[58:59] sc1
	global_load_dword v14, v16, s[60:61] sc1
	s_mov_b64 s[62:63], -1
	s_mov_b64 s[64:65], -1
	s_waitcnt vmcnt(14)
	v_add_u32_e32 v17, v0, v15
	s_waitcnt vmcnt(13)
	v_add_u32_e32 v17, v17, v1
	s_waitcnt vmcnt(12)
	v_add_u32_e32 v17, v17, v2
	s_waitcnt vmcnt(11)
	v_add_u32_e32 v17, v17, v3
	s_waitcnt vmcnt(10)
	v_add_u32_e32 v17, v17, v4
	s_waitcnt vmcnt(9)
	v_add_u32_e32 v17, v17, v5
	s_waitcnt vmcnt(8)
	v_add_u32_e32 v17, v17, v6
	s_waitcnt vmcnt(7)
	v_add_u32_e32 v17, v17, v7
	s_waitcnt vmcnt(6)
	v_add_u32_e32 v17, v17, v8
	s_waitcnt vmcnt(5)
	v_add_u32_e32 v17, v17, v9
	s_waitcnt vmcnt(4)
	v_add_u32_e32 v17, v17, v10
	s_waitcnt vmcnt(3)
	v_add_u32_e32 v17, v17, v11
	s_waitcnt vmcnt(2)
	v_add_u32_e32 v17, v17, v12
	s_waitcnt vmcnt(1)
	v_add_u32_e32 v17, v17, v13
	s_waitcnt vmcnt(0)
	v_add_u32_e32 v17, v17, v14
	v_cmp_eq_u32_e32 vcc, s1, v17
	s_cbranch_vccnz .LBB0_1242
	s_and_b32 s20, s2, 0xff
	s_cmp_eq_u32 s20, 0
	s_mov_b64 s[66:67], -1
	s_nop 0
	s_cbranch_scc0 .LBB0_1247
	global_load_dword v17, v16, s[10:11] sc1
	s_waitcnt vmcnt(0)
	v_cmp_eq_u32_e32 vcc, 0, v17
	s_cbranch_vccnz .LBB0_1249
	s_mov_b64 s[66:67], 0

.LBB0_1378:
	global_load_dword v15, v16, s[14:15] sc1
	s_waitcnt lgkmcnt(0)
	global_load_dword v0, v16, s[16:17] sc1
	global_load_dword v1, v16, s[24:25] sc1
	global_load_dword v2, v16, s[26:27] sc1
	global_load_dword v3, v16, s[28:29] sc1
	global_load_dword v4, v16, s[30:31] sc1
	global_load_dword v5, v16, s[36:37] sc1
	global_load_dword v6, v16, s[38:39] sc1
	global_load_dword v7, v16, s[46:47] sc1
	global_load_dword v8, v16, s[50:51] sc1
	global_load_dword v9, v16, s[52:53] sc1
	global_load_dword v10, v16, s[54:55] sc1
	global_load_dword v11, v16, s[56:57] sc1
	global_load_dword v12, v16, s[58:59] sc1
	global_load_dword v13, v16, s[60:61] sc1
	global_load_dword v14, v16, s[62:63] sc1
	s_mov_b64 s[64:65], -1
	s_mov_b64 s[66:67], -1
	s_waitcnt vmcnt(14)
	v_add_u32_e32 v17, v0, v15
	s_waitcnt vmcnt(13)
	v_add_u32_e32 v17, v17, v1
	s_waitcnt vmcnt(12)
	v_add_u32_e32 v17, v17, v2
	s_waitcnt vmcnt(11)
	v_add_u32_e32 v17, v17, v3
	s_waitcnt vmcnt(10)
	v_add_u32_e32 v17, v17, v4
	s_waitcnt vmcnt(9)
	v_add_u32_e32 v17, v17, v5
	s_waitcnt vmcnt(8)
	v_add_u32_e32 v17, v17, v6
	s_waitcnt vmcnt(7)
	v_add_u32_e32 v17, v17, v7
	s_waitcnt vmcnt(6)
	v_add_u32_e32 v17, v17, v8
	s_waitcnt vmcnt(5)
	v_add_u32_e32 v17, v17, v9
	s_waitcnt vmcnt(4)
	v_add_u32_e32 v17, v17, v10
	s_waitcnt vmcnt(3)
	v_add_u32_e32 v17, v17, v11
	s_waitcnt vmcnt(2)
	v_add_u32_e32 v17, v17, v12
	s_waitcnt vmcnt(1)
	v_add_u32_e32 v17, v17, v13
	s_waitcnt vmcnt(0)
	v_add_u32_e32 v17, v17, v14
	v_cmp_eq_u32_e32 vcc, s1, v17
	s_cbranch_vccnz .LBB0_1377
	s_and_b32 s20, s2, 0xff
	s_cmp_eq_u32 s20, 0
	s_mov_b64 s[68:69], -1
	s_nop 0
	s_cbranch_scc0 .LBB0_1382
	global_load_dword v17, v16, s[12:13] sc1
	s_waitcnt vmcnt(0)
	v_cmp_eq_u32_e32 vcc, 0, v17
	s_cbranch_vccnz .LBB0_1384
	s_mov_b64 s[68:69], 0

.LBB0_1396:
	s_and_b32 s1, s0, 0xff
	s_mov_b64 s[36:37], -1
	s_cmp_lg_u32 s1, 0
	s_mov_b64 s[46:47], -1
	s_nop 0
	s_cbranch_scc1 .LBB0_1399
	global_load_dword v2, v0, s[24:25] sc1
	s_waitcnt vmcnt(0)
	v_cmp_eq_u32_e32 vcc, 0, v2
	s_cbranch_vccnz .LBB0_1401
	s_mov_b64 s[46:47], 0
	s_mov_b64 s[38:39], -1

.LBB0_1413:
	s_and_b32 s1, s0, 0xff
	s_cmp_lg_u32 s1, 0
	s_mov_b64 s[36:37], -1
	s_nop 0
	s_cbranch_scc1 .LBB0_1416
	global_load_dword v1, v0, s[24:25] sc1
	s_waitcnt vmcnt(0)
	v_cmp_eq_u32_e32 vcc, 0, v1
	s_cbranch_vccnz .LBB0_1418
	s_mov_b64 s[36:37], 0
	s_mov_b64 s[30:31], -1

.LBB0_1523:
	global_load_dword v15, v16, s[14:15] sc1
	s_waitcnt lgkmcnt(0)
	global_load_dword v0, v16, s[16:17] sc1
	global_load_dword v1, v16, s[24:25] sc1
	global_load_dword v2, v16, s[26:27] sc1
	global_load_dword v3, v16, s[28:29] sc1
	global_load_dword v4, v16, s[30:31] sc1
	global_load_dword v5, v16, s[38:39] sc1
	global_load_dword v6, v16, s[42:43] sc1
	global_load_dword v7, v16, s[44:45] sc1
	global_load_dword v8, v16, s[46:47] sc1
	global_load_dword v9, v16, s[50:51] sc1
	global_load_dword v10, v16, s[52:53] sc1
	global_load_dword v11, v16, s[54:55] sc1
	global_load_dword v12, v16, s[56:57] sc1
	global_load_dword v13, v16, s[58:59] sc1
	global_load_dword v14, v16, s[60:61] sc1
	s_mov_b64 s[62:63], -1
	s_mov_b64 s[64:65], -1
	s_waitcnt vmcnt(14)
	v_add_u32_e32 v17, v0, v15
	s_waitcnt vmcnt(13)
	v_add_u32_e32 v17, v17, v1
	s_waitcnt vmcnt(12)
	v_add_u32_e32 v17, v17, v2
	s_waitcnt vmcnt(11)
	v_add_u32_e32 v17, v17, v3
	s_waitcnt vmcnt(10)
	v_add_u32_e32 v17, v17, v4
	s_waitcnt vmcnt(9)
	v_add_u32_e32 v17, v17, v5
	s_waitcnt vmcnt(8)
	v_add_u32_e32 v17, v17, v6
	s_waitcnt vmcnt(7)
	v_add_u32_e32 v17, v17, v7
	s_waitcnt vmcnt(6)
	v_add_u32_e32 v17, v17, v8
	s_waitcnt vmcnt(5)
	v_add_u32_e32 v17, v17, v9
	s_waitcnt vmcnt(4)
	v_add_u32_e32 v17, v17, v10
	s_waitcnt vmcnt(3)
	v_add_u32_e32 v17, v17, v11
	s_waitcnt vmcnt(2)
	v_add_u32_e32 v17, v17, v12
	s_waitcnt vmcnt(1)
	v_add_u32_e32 v17, v17, v13
	s_waitcnt vmcnt(0)
	v_add_u32_e32 v17, v17, v14
	v_cmp_eq_u32_e32 vcc, s1, v17
	s_cbranch_vccnz .LBB0_1522
	s_and_b32 s20, s2, 0xff
	s_cmp_eq_u32 s20, 0
	s_mov_b64 s[66:67], -1
	s_nop 0
	s_cbranch_scc0 .LBB0_1527
	global_load_dword v17, v16, s[12:13] sc1
	s_waitcnt vmcnt(0)
	v_cmp_eq_u32_e32 vcc, 0, v17
	s_cbranch_vccnz .LBB0_1529
	s_mov_b64 s[66:67], 0

.LBB0_1541:
	s_and_b32 s1, s0, 0xff
	s_mov_b64 s[38:39], -1
	s_cmp_lg_u32 s1, 0
	s_mov_b64 s[44:45], -1
	s_nop 0
	s_cbranch_scc1 .LBB0_1544
	global_load_dword v2, v0, s[24:25] sc1
	s_waitcnt vmcnt(0)
	v_cmp_eq_u32_e32 vcc, 0, v2
	s_cbranch_vccnz .LBB0_1546
	s_mov_b64 s[44:45], 0
	s_mov_b64 s[42:43], -1

.LBB0_1558:
	s_and_b32 s1, s0, 0xff
	s_cmp_lg_u32 s1, 0
	s_mov_b64 s[38:39], -1
	s_nop 0
	s_cbranch_scc1 .LBB0_1561
	global_load_dword v1, v0, s[24:25] sc1
	s_waitcnt vmcnt(0)
	v_cmp_eq_u32_e32 vcc, 0, v1
	s_cbranch_vccnz .LBB0_1563
	s_mov_b64 s[38:39], 0
	s_mov_b64 s[30:31], -1

.LBB0_1685:
	global_load_dword v15, v16, s[14:15] sc1
	s_waitcnt lgkmcnt(0)
	global_load_dword v0, v16, s[16:17] sc1
	global_load_dword v1, v16, s[18:19] sc1
	global_load_dword v2, v16, s[24:25] sc1
	global_load_dword v3, v16, s[26:27] sc1
	global_load_dword v4, v16, s[28:29] sc1
	global_load_dword v5, v16, s[34:35] sc1
	global_load_dword v6, v16, s[38:39] sc1
	global_load_dword v7, v16, s[40:41] sc1
	global_load_dword v8, v16, s[42:43] sc1
	global_load_dword v9, v16, s[44:45] sc1
	global_load_dword v10, v16, s[46:47] sc1
	global_load_dword v11, v16, s[48:49] sc1
	global_load_dword v12, v16, s[50:51] sc1
	global_load_dword v13, v16, s[52:53] sc1
	global_load_dword v14, v16, s[54:55] sc1
	s_mov_b64 s[56:57], -1
	s_mov_b64 s[58:59], -1
	s_waitcnt vmcnt(14)
	v_add_u32_e32 v17, v0, v15
	s_waitcnt vmcnt(13)
	v_add_u32_e32 v17, v17, v1
	s_waitcnt vmcnt(12)
	v_add_u32_e32 v17, v17, v2
	s_waitcnt vmcnt(11)
	v_add_u32_e32 v17, v17, v3
	s_waitcnt vmcnt(10)
	v_add_u32_e32 v17, v17, v4
	s_waitcnt vmcnt(9)
	v_add_u32_e32 v17, v17, v5
	s_waitcnt vmcnt(8)
	v_add_u32_e32 v17, v17, v6
	s_waitcnt vmcnt(7)
	v_add_u32_e32 v17, v17, v7
	s_waitcnt vmcnt(6)
	v_add_u32_e32 v17, v17, v8
	s_waitcnt vmcnt(5)
	v_add_u32_e32 v17, v17, v9
	s_waitcnt vmcnt(4)
	v_add_u32_e32 v17, v17, v10
	s_waitcnt vmcnt(3)
	v_add_u32_e32 v17, v17, v11
	s_waitcnt vmcnt(2)
	v_add_u32_e32 v17, v17, v12
	s_waitcnt vmcnt(1)
	v_add_u32_e32 v17, v17, v13
	s_waitcnt vmcnt(0)
	v_add_u32_e32 v17, v17, v14
	v_cmp_eq_u32_e32 vcc, s2, v17
	s_cbranch_vccnz .LBB0_1684
	s_and_b32 s21, s20, 0xff
	s_cmp_eq_u32 s21, 0
	s_mov_b64 s[60:61], -1
	s_nop 0
	s_cbranch_scc0 .LBB0_1689
	global_load_dword v17, v16, s[12:13] sc1
	s_waitcnt vmcnt(0)
	v_cmp_eq_u32_e32 vcc, 0, v17
	s_cbranch_vccnz .LBB0_1691
	s_mov_b64 s[60:61], 0

.LBB0_1703:
	s_and_b32 s2, s1, 0xff
	s_mov_b64 s[34:35], -1
	s_cmp_lg_u32 s2, 0
	s_mov_b64 s[40:41], -1
	s_nop 0
	s_cbranch_scc1 .LBB0_1706
	global_load_dword v2, v0, s[18:19] sc1
	s_waitcnt vmcnt(0)
	v_cmp_eq_u32_e32 vcc, 0, v2
	s_cbranch_vccnz .LBB0_1708
	s_mov_b64 s[40:41], 0
	s_mov_b64 s[38:39], -1

.LBB0_1720:
	s_and_b32 s2, s1, 0xff
	s_cmp_lg_u32 s2, 0
	s_mov_b64 s[34:35], -1
	s_nop 0
	s_cbranch_scc1 .LBB0_1723
	global_load_dword v1, v0, s[18:19] sc1
	s_waitcnt vmcnt(0)
	v_cmp_eq_u32_e32 vcc, 0, v1
	s_cbranch_vccnz .LBB0_1725
	s_mov_b64 s[34:35], 0
	s_mov_b64 s[30:31], -1

.LBB0_1828:
	global_load_dword v15, v16, s[12:13] sc1
	s_waitcnt lgkmcnt(0)
	global_load_dword v0, v16, s[14:15] sc1
	global_load_dword v1, v16, s[16:17] sc1
	global_load_dword v2, v16, s[18:19] sc1
	global_load_dword v3, v16, s[24:25] sc1
	global_load_dword v4, v16, s[26:27] sc1
	global_load_dword v5, v16, s[28:29] sc1
	global_load_dword v6, v16, s[34:35] sc1
	global_load_dword v7, v16, s[36:37] sc1
	global_load_dword v8, v16, s[38:39] sc1
	global_load_dword v9, v16, s[40:41] sc1
	global_load_dword v10, v16, s[42:43] sc1
	global_load_dword v11, v16, s[44:45] sc1
	global_load_dword v12, v16, s[46:47] sc1
	global_load_dword v13, v16, s[48:49] sc1
	global_load_dword v14, v16, s[50:51] sc1
	s_mov_b64 s[52:53], -1
	s_mov_b64 s[54:55], -1
	s_waitcnt vmcnt(14)
	v_add_u32_e32 v17, v0, v15
	s_waitcnt vmcnt(13)
	v_add_u32_e32 v17, v17, v1
	s_waitcnt vmcnt(12)
	v_add_u32_e32 v17, v17, v2
	s_waitcnt vmcnt(11)
	v_add_u32_e32 v17, v17, v3
	s_waitcnt vmcnt(10)
	v_add_u32_e32 v17, v17, v4
	s_waitcnt vmcnt(9)
	v_add_u32_e32 v17, v17, v5
	s_waitcnt vmcnt(8)
	v_add_u32_e32 v17, v17, v6
	s_waitcnt vmcnt(7)
	v_add_u32_e32 v17, v17, v7
	s_waitcnt vmcnt(6)
	v_add_u32_e32 v17, v17, v8
	s_waitcnt vmcnt(5)
	v_add_u32_e32 v17, v17, v9
	s_waitcnt vmcnt(4)
	v_add_u32_e32 v17, v17, v10
	s_waitcnt vmcnt(3)
	v_add_u32_e32 v17, v17, v11
	s_waitcnt vmcnt(2)
	v_add_u32_e32 v17, v17, v12
	s_waitcnt vmcnt(1)
	v_add_u32_e32 v17, v17, v13
	s_waitcnt vmcnt(0)
	v_add_u32_e32 v17, v17, v14
	v_cmp_eq_u32_e32 vcc, s1, v17
	s_cbranch_vccnz .LBB0_1827
	s_and_b32 s3, s2, 0xff
	s_cmp_eq_u32 s3, 0
	s_mov_b64 s[56:57], -1
	s_nop 0
	s_cbranch_scc0 .LBB0_1832
	global_load_dword v17, v16, s[10:11] sc1
	s_waitcnt vmcnt(0)
	v_cmp_eq_u32_e32 vcc, 0, v17
	s_cbranch_vccnz .LBB0_1834
	s_mov_b64 s[56:57], 0

.LBB0_1846:
	s_and_b32 s1, s0, 0xff
	s_mov_b64 s[28:29], -1
	s_cmp_lg_u32 s1, 0
	s_mov_b64 s[36:37], -1
	s_nop 0
	s_cbranch_scc1 .LBB0_1849
	global_load_dword v2, v0, s[16:17] sc1
	s_waitcnt vmcnt(0)
	v_cmp_eq_u32_e32 vcc, 0, v2
	s_cbranch_vccnz .LBB0_1851
	s_mov_b64 s[36:37], 0
	s_mov_b64 s[34:35], -1

.LBB0_1863:
	s_and_b32 s1, s0, 0xff
	s_cmp_lg_u32 s1, 0
	s_mov_b64 s[30:31], -1
	s_nop 0
	s_cbranch_scc1 .LBB0_1866
	global_load_dword v1, v0, s[16:17] sc1
	s_waitcnt vmcnt(0)
	v_cmp_eq_u32_e32 vcc, 0, v1
	s_cbranch_vccnz .LBB0_1868
	s_mov_b64 s[30:31], 0
	s_mov_b64 s[28:29], -1

.LBB0_1918:
	global_load_dword v15, v16, s[12:13] sc1
	s_waitcnt lgkmcnt(0)
	global_load_dword v0, v16, s[16:17] sc1
	global_load_dword v1, v16, s[18:19] sc1
	global_load_dword v2, v16, s[24:25] sc1
	global_load_dword v3, v16, s[26:27] sc1
	global_load_dword v4, v16, s[28:29] sc1
	global_load_dword v5, v16, s[30:31] sc1
	global_load_dword v6, v16, s[34:35] sc1
	global_load_dword v7, v16, s[36:37] sc1
	global_load_dword v8, v16, s[38:39] sc1
	global_load_dword v9, v16, s[40:41] sc1
	global_load_dword v10, v16, s[42:43] sc1
	global_load_dword v11, v16, s[44:45] sc1
	global_load_dword v12, v16, s[46:47] sc1
	global_load_dword v13, v16, s[48:49] sc1
	global_load_dword v14, v16, s[50:51] sc1
	s_mov_b64 s[52:53], -1
	s_mov_b64 s[54:55], -1
	s_waitcnt vmcnt(14)
	v_add_u32_e32 v17, v0, v15
	s_waitcnt vmcnt(13)
	v_add_u32_e32 v17, v17, v1
	s_waitcnt vmcnt(12)
	v_add_u32_e32 v17, v17, v2
	s_waitcnt vmcnt(11)
	v_add_u32_e32 v17, v17, v3
	s_waitcnt vmcnt(10)
	v_add_u32_e32 v17, v17, v4
	s_waitcnt vmcnt(9)
	v_add_u32_e32 v17, v17, v5
	s_waitcnt vmcnt(8)
	v_add_u32_e32 v17, v17, v6
	s_waitcnt vmcnt(7)
	v_add_u32_e32 v17, v17, v7
	s_waitcnt vmcnt(6)
	v_add_u32_e32 v17, v17, v8
	s_waitcnt vmcnt(5)
	v_add_u32_e32 v17, v17, v9
	s_waitcnt vmcnt(4)
	v_add_u32_e32 v17, v17, v10
	s_waitcnt vmcnt(3)
	v_add_u32_e32 v17, v17, v11
	s_waitcnt vmcnt(2)
	v_add_u32_e32 v17, v17, v12
	s_waitcnt vmcnt(1)
	v_add_u32_e32 v17, v17, v13
	s_waitcnt vmcnt(0)
	v_add_u32_e32 v17, v17, v14
	v_cmp_eq_u32_e32 vcc, s1, v17
	s_cbranch_vccnz .LBB0_1917
	s_and_b32 s3, s2, 0xff
	s_cmp_eq_u32 s3, 0
	s_mov_b64 s[56:57], -1
	s_nop 0
	s_cbranch_scc0 .LBB0_1922
	global_load_dword v17, v16, s[10:11] sc1
	s_waitcnt vmcnt(0)
	v_cmp_eq_u32_e32 vcc, 0, v17
	s_cbranch_vccnz .LBB0_1924
	s_mov_b64 s[56:57], 0

.LBB0_1936:
	s_and_b32 s1, s0, 0xff
	s_mov_b64 s[30:31], -1
	s_cmp_lg_u32 s1, 0
	s_mov_b64 s[36:37], -1
	s_nop 0
	s_cbranch_scc1 .LBB0_1939
	global_load_dword v2, v0, s[18:19] sc1
	s_waitcnt vmcnt(0)
	v_cmp_eq_u32_e32 vcc, 0, v2
	s_cbranch_vccnz .LBB0_1941
	s_mov_b64 s[36:37], 0
	s_mov_b64 s[34:35], -1

.LBB0_1990:
	global_load_dword v15, v16, s[10:11] sc1
	s_waitcnt lgkmcnt(0)
	global_load_dword v0, v16, s[14:15] sc1
	global_load_dword v1, v16, s[16:17] sc1
	global_load_dword v2, v16, s[18:19] sc1
	global_load_dword v3, v16, s[24:25] sc1
	global_load_dword v4, v16, s[26:27] sc1
	global_load_dword v5, v16, s[28:29] sc1
	global_load_dword v6, v16, s[30:31] sc1
	global_load_dword v7, v16, s[34:35] sc1
	global_load_dword v8, v16, s[36:37] sc1
	global_load_dword v9, v16, s[38:39] sc1
	global_load_dword v10, v16, s[40:41] sc1
	global_load_dword v11, v16, s[42:43] sc1
	global_load_dword v12, v16, s[44:45] sc1
	global_load_dword v13, v16, s[46:47] sc1
	global_load_dword v14, v16, s[48:49] sc1
	s_mov_b64 s[50:51], -1
	s_mov_b64 s[52:53], -1
	s_waitcnt vmcnt(14)
	v_add_u32_e32 v17, v0, v15
	s_waitcnt vmcnt(13)
	v_add_u32_e32 v17, v17, v1
	s_waitcnt vmcnt(12)
	v_add_u32_e32 v17, v17, v2
	s_waitcnt vmcnt(11)
	v_add_u32_e32 v17, v17, v3
	s_waitcnt vmcnt(10)
	v_add_u32_e32 v17, v17, v4
	s_waitcnt vmcnt(9)
	v_add_u32_e32 v17, v17, v5
	s_waitcnt vmcnt(8)
	v_add_u32_e32 v17, v17, v6
	s_waitcnt vmcnt(7)
	v_add_u32_e32 v17, v17, v7
	s_waitcnt vmcnt(6)
	v_add_u32_e32 v17, v17, v8
	s_waitcnt vmcnt(5)
	v_add_u32_e32 v17, v17, v9
	s_waitcnt vmcnt(4)
	v_add_u32_e32 v17, v17, v10
	s_waitcnt vmcnt(3)
	v_add_u32_e32 v17, v17, v11
	s_waitcnt vmcnt(2)
	v_add_u32_e32 v17, v17, v12
	s_waitcnt vmcnt(1)
	v_add_u32_e32 v17, v17, v13
	s_waitcnt vmcnt(0)
	v_add_u32_e32 v17, v17, v14
	v_cmp_eq_u32_e32 vcc, s1, v17
	s_cbranch_vccnz .LBB0_1989
	s_and_b32 s3, s2, 0xff
	s_cmp_eq_u32 s3, 0
	s_mov_b64 s[54:55], -1
	s_nop 0
	s_cbranch_scc0 .LBB0_1994
	global_load_dword v17, v16, s[8:9] sc1
	s_waitcnt vmcnt(0)
	v_cmp_eq_u32_e32 vcc, 0, v17
	s_cbranch_vccnz .LBB0_1996
	s_mov_b64 s[54:55], 0

.LBB0_2008:
	s_and_b32 s1, s0, 0xff
	s_mov_b64 s[28:29], -1
	s_cmp_lg_u32 s1, 0
	s_mov_b64 s[34:35], -1
	s_nop 0
	s_cbranch_scc1 .LBB0_2011
	global_load_dword v2, v0, s[16:17] sc1
	s_waitcnt vmcnt(0)
	v_cmp_eq_u32_e32 vcc, 0, v2
	s_cbranch_vccnz .LBB0_2013
	s_mov_b64 s[34:35], 0
	s_mov_b64 s[30:31], -1

.LBB0_2025:
	s_and_b32 s1, s0, 0xff
	s_cmp_lg_u32 s1, 0
	s_mov_b64 s[28:29], -1
	s_nop 0
	s_cbranch_scc1 .LBB0_2028
	global_load_dword v1, v0, s[16:17] sc1
	s_waitcnt vmcnt(0)
	v_cmp_eq_u32_e32 vcc, 0, v1
	s_cbranch_vccnz .LBB0_2030
	s_mov_b64 s[28:29], 0
	s_mov_b64 s[26:27], -1

.LBB0_2080:
	global_load_dword v15, v16, s[6:7] sc1
	s_waitcnt lgkmcnt(0)
	global_load_dword v0, v16, s[10:11] sc1
	global_load_dword v1, v16, s[12:13] sc1
	global_load_dword v2, v16, s[14:15] sc1
	global_load_dword v3, v16, s[16:17] sc1
	global_load_dword v4, v16, s[18:19] sc1
	global_load_dword v5, v16, s[20:21] sc1
	global_load_dword v6, v16, s[22:23] sc1
	global_load_dword v7, v16, s[24:25] sc1
	global_load_dword v8, v16, s[26:27] sc1
	global_load_dword v9, v16, s[28:29] sc1
	global_load_dword v10, v16, s[30:31] sc1
	global_load_dword v11, v16, s[34:35] sc1
	global_load_dword v12, v16, s[36:37] sc1
	global_load_dword v13, v16, s[38:39] sc1
	global_load_dword v14, v16, s[40:41] sc1
	s_mov_b64 s[42:43], -1
	s_mov_b64 s[44:45], -1
	s_waitcnt vmcnt(14)
	v_add_u32_e32 v17, v0, v15
	s_waitcnt vmcnt(13)
	v_add_u32_e32 v17, v17, v1
	s_waitcnt vmcnt(12)
	v_add_u32_e32 v17, v17, v2
	s_waitcnt vmcnt(11)
	v_add_u32_e32 v17, v17, v3
	s_waitcnt vmcnt(10)
	v_add_u32_e32 v17, v17, v4
	s_waitcnt vmcnt(9)
	v_add_u32_e32 v17, v17, v5
	s_waitcnt vmcnt(8)
	v_add_u32_e32 v17, v17, v6
	s_waitcnt vmcnt(7)
	v_add_u32_e32 v17, v17, v7
	s_waitcnt vmcnt(6)
	v_add_u32_e32 v17, v17, v8
	s_waitcnt vmcnt(5)
	v_add_u32_e32 v17, v17, v9
	s_waitcnt vmcnt(4)
	v_add_u32_e32 v17, v17, v10
	s_waitcnt vmcnt(3)
	v_add_u32_e32 v17, v17, v11
	s_waitcnt vmcnt(2)
	v_add_u32_e32 v17, v17, v12
	s_waitcnt vmcnt(1)
	v_add_u32_e32 v17, v17, v13
	s_waitcnt vmcnt(0)
	v_add_u32_e32 v17, v17, v14
	v_cmp_eq_u32_e32 vcc, s1, v17
	s_cbranch_vccnz .LBB0_2079
	s_and_b32 s42, s33, 0xff
	s_cmp_eq_u32 s42, 0
	s_mov_b64 s[42:43], -1
	s_mov_b64 s[46:47], -1
	s_nop 0
	s_cbranch_scc0 .LBB0_2084
	global_load_dword v17, v16, s[4:5] sc1
	s_waitcnt vmcnt(0)
	v_cmp_eq_u32_e32 vcc, 0, v17
	s_cbranch_vccnz .LBB0_2086
	s_mov_b64 s[46:47], 0

.LBB0_2098:
	s_and_b32 s1, s0, 0xff
	s_mov_b64 s[20:21], -1
	s_cmp_lg_u32 s1, 0
	s_mov_b64 s[24:25], -1
	s_nop 0
	s_cbranch_scc1 .LBB0_2101
	global_load_dword v2, v0, s[12:13] sc1
	s_waitcnt vmcnt(0)
	v_cmp_eq_u32_e32 vcc, 0, v2
	s_cbranch_vccnz .LBB0_2103
	s_mov_b64 s[24:25], 0
	s_mov_b64 s[22:23], -1

.LBB0_2115:
	s_and_b32 s1, s0, 0xff
	s_cmp_lg_u32 s1, 0
	s_mov_b64 s[20:21], -1
	s_nop 0
	s_cbranch_scc1 .LBB0_2118
	global_load_dword v1, v0, s[12:13] sc1
	s_waitcnt vmcnt(0)
	v_cmp_eq_u32_e32 vcc, 0, v1
	s_cbranch_vccnz .LBB0_2120
	s_mov_b64 s[20:21], 0
	s_mov_b64 s[18:19], -1
